# pool GEMM tiles assigned by unit-queue finishing rank (final ticket - 2052) instead of block id: early finishers take the pool tiles
# speedup vs baseline: 1.0066x; 1.0003x over previous
.LBB0_799:
	s_sub_i32 s98, s36, 0x804
	s_add_u32 s0, s18, 0xfca8000
	s_addc_u32 s1, s19, 0
	v_readlane_b32 s4, v250, 30
	s_add_u32 s36, s18, 0x24128000
	v_readlane_b32 s5, v250, 31
	s_addc_u32 s37, s19, 0
	s_lshl_b64 s[38:39], s[4:5], 12
	s_mov_b64 s[40:41], s[18:19]
	v_readlane_b32 s4, v252, 19
	v_readlane_b32 s8, v252, 23
	v_readlane_b32 s9, v252, 24
	s_add_u32 s38, s8, s38
	v_readlane_b32 s10, v252, 25
	v_readlane_b32 s11, v252, 26
	s_addc_u32 s39, s9, s39
	s_mov_b32 s4, s98
	s_mov_b64 s[10:11], s[40:41]
	s_cmpk_gt_i32 s4, 0x7f
	v_readlane_b32 s5, v252, 20
	v_readlane_b32 s6, v252, 21
	v_readlane_b32 s7, v252, 22
	v_readlane_b32 s12, v252, 27
	v_readlane_b32 s13, v252, 28
	v_readlane_b32 s14, v252, 29
	v_readlane_b32 s15, v252, 30
	v_readlane_b32 s16, v252, 31
	v_readlane_b32 s17, v252, 32
	v_readlane_b32 s18, v252, 33
	v_readlane_b32 s19, v252, 34
	s_cbranch_scc1 .LBB0_806
	s_add_u32 s48, s10, 0xec28000
	s_mov_b32 s58, s98
	s_addc_u32 s49, s11, 0
	s_lshl_b32 s40, s58, 8
	v_readlane_b32 s4, v250, 32
	s_or_b32 s50, s40, 0xb0
	s_lshl_b32 s51, s4, 8
	s_branch .LBB0_802
